# sample diff-attn unit: 2-deep K/V prefetch with second VGPR set, map-1 waves take tiles (tt+2)&3
# speedup vs baseline: 1.0037x; 1.0037x over previous
; #define GASP __attribute__((address_space(1)))
;     ...
;     const int S = SAMPLE ? PAST + DECS : SEQ, qpos0 = SAMPLE ? PAST : qi * 128 + sub * 32, rowq0 = SAMPLE ? NP + b * 32 : b * SEQ + qi * 128 + sub * 32;
;     const int NT = SAMPLE ? (PAST + DECS + 63) / 64 : 2 * qi + 2;
;     const int ntw = SAMPLE ? NT : min(NT, (qpos0 >> 6) + 1);
;     const float slope2 = exp2f(-2.f * (float)(h + 1)) * LOG2E;
;     bf16x8 qf[4];
;     { const bf16_t* qp = QB + (size_t)(rowq0 + r) * 512 + h * 128 + map * 64 + hi * 8;
; #pragma unroll
;       for (int d0 = 0; d0 < 4; ++d0) qf[d0] = *(const GASP bf16x8*)(qp + d0 * 16); }
;     f32x16 OT[NEB];
; #pragma unroll
;     for (int e = 0; e < NEB; ++e)
; #pragma unroll
;         for (int i = 0; i < 16; ++i) OT[e][i] = 0.f;
;     float m = -1e30f, l = 0.f;
;     const int lkey = tid >> 3, lc = tid & 7;
;     u32x4 pfA[NPF], pfB[SAMPLE ? 1 : NPF];
;     const float* ck = p.in[2]; const float* cv = p.in[3];
;     ...
;     const int i16 = lane & 15;
;     const int vlane_off = (4 * hi + (i16 >> 2)) * DA_VRS + (16 * ((lane >> 4) & 1) + 4 * (i16 & 3)) * 2;
;     const int tq = qpos0 + r;
;     ...
;     DA_ISSUE(pfA, 0); DA_WRITE(pfA, 0, 0);
;     if constexpr (SAMPLE) {
;         asm volatile("" : "+v"(qf[0]), "+v"(qf[1]), "+v"(qf[2]), "+v"(qf[3]));
;         __syncthreads();
; #pragma unroll 1
;         for (int tt = 0; tt < NT; ++tt) {
;             if (tt + 1 < NT) DA_ISSUE(pfA, tt + 1);
.LBB0_945:
	s_andn2_b64 vcc, exec, s[6:7]
	s_cbranch_vccnz .LBB0_869
	s_ashr_i32 s5, s4, 2
	v_mov_b32_e32 v0, v208
	s_lshl_b32 s56, s5, 5
	s_waitcnt vmcnt(4)
	v_ashrrev_i32_e32 v18, 3, v0
	s_lshl_b32 s41, s5, 12
	s_and_b32 s8, s4, 3
	v_and_b32_e32 v175, 31, v0
	s_add_i32 s4, s56, 0x8000
	v_add_u32_e32 v4, s41, v18
	v_or_b32_e32 v162, s4, v175
	s_lshl_b32 s4, s8, 7
	v_and_b32_e32 v8, 7, v0
	v_ashrrev_i32_e32 v5, 31, v4
	v_lshlrev_b64 v[4:5], 11, v[4:5]
	v_lshl_or_b32 v164, v8, 4, s4
	v_readfirstlane_b32 s33, v0
	v_ashrrev_i32_e32 v163, 31, v162
	v_lshl_or_b32 v4, v164, 2, v4
	s_ashr_i32 s40, s33, 8
	v_lshlrev_b64 v[2:3], 10, v[162:163]
	v_lshl_add_u64 v[6:7], s[24:25], 0, v[4:5]
	v_lshl_add_u64 v[4:5], s[26:27], 0, v[4:5]
	global_load_dwordx4 v[112:115], v[6:7], off offset:16
	global_load_dwordx4 v[116:119], v[6:7], off
	v_lshl_add_u64 v[2:3], s[70:71], 0, v[2:3]
	s_lshl_b32 s30, s8, 8
	global_load_dwordx4 v[120:123], v[6:7], off offset:48
	global_load_dwordx4 v[124:127], v[6:7], off offset:32
	global_load_dwordx4 v[128:131], v[4:5], off offset:16
	global_load_dwordx4 v[136:139], v[4:5], off
	s_lshl_b32 s6, s40, 6
	global_load_dwordx4 v[132:135], v[4:5], off offset:48
	global_load_dwordx4 v[140:143], v[4:5], off offset:32
	v_bfe_u32 v176, v0, 5, 1
	v_lshl_add_u64 v[2:3], v[2:3], 0, s[30:31]
	s_ashr_i32 s7, s6, 31
	v_lshl_add_u64 v[2:3], s[6:7], 1, v[2:3]
	v_lshlrev_b32_e32 v166, 4, v176
	v_mov_b32_e32 v167, v1
	v_lshl_add_u64 v[2:3], v[2:3], 0, v[166:167]
	global_load_dwordx4 v[144:147], v[2:3], off offset:96
	global_load_dwordx4 v[148:151], v[2:3], off offset:64
	global_load_dwordx4 v[152:155], v[2:3], off offset:32
	global_load_dwordx4 v[156:159], v[2:3], off
	s_not_b32 s5, s8
	v_lshrrev_b32_e32 v2, 2, v0
	v_and_b32_e32 v3, 16, v0
	v_lshlrev_b32_e32 v4, 2, v0
	v_bfe_u32 v5, v0, 2, 1
	v_lshlrev_b32_e32 v0, 5, v0
	s_movk_i32 s6, 0x2400
	s_lshl_b32 s5, s5, 1
	v_lshlrev_b32_e32 v167, 2, v176
	v_and_or_b32 v3, v4, 12, v3
	v_mad_u32_u24 v4, v5, s6, 0
	v_mul_lo_u32 v177, v18, s90
	v_and_b32_e32 v178, 0x60, v0
	v_ldexp_f32 v6, 1.0, s5
	v_mul_u32_u24_e32 v169, 0x2400, v5
	v_mul_lo_u32 v179, v18, s88
	v_lshlrev_b32_e32 v180, 5, v8
	v_and_or_b32 v0, v2, 3, v167
	v_lshlrev_b32_e32 v182, 1, v3
	v_add3_u32 v19, v4, v177, v178
	v_mul_f32_e32 v181, 0x3fb8aa3b, v6
	v_add3_u32 v20, 0, v179, v180
	v_mul_u32_u24_e32 v183, 0x140, v0
	v_readfirstlane_b32 s8, v181
	v_add_u32_e32 v186, 64, v18
	v_mov_b32_e32 v0, v1
	s_lshr_b32 s5, s33, 6
	s_bfe_u32 s30, s33, 0x20006
	s_lshl_b32 s98, s40, 1
	s_xor_b32 s30, s30, s98
	s_addk_i32 s56, 0x7000
	v_mul_u32_u24_e32 v184, 0x90, v175
	s_mov_b32 s9, s8
	s_mov_b32 s57, s8
	s_mov_b32 s84, s8
	s_mov_b32 s85, s8
	s_mov_b32 s86, s8
	s_mov_b32 s87, s8
	s_mov_b32 s91, s8
	s_mov_b32 s92, s8
	s_mov_b32 s93, s8
	s_mov_b32 s94, s8
	s_mov_b32 s95, s8
	s_mov_b32 s96, s8
	s_mov_b32 s97, s8
	s_mov_b32 s14, s8
	s_mov_b32 s15, s8
	v_sub_u32_e32 v185, v175, v167
	s_mov_b32 s34, 0
	v_mov_b32_e32 v168, 0xf149f2ca
	v_mov_b32_e32 v187, 0
	s_mov_b32 s28, 0
	s_waitcnt vmcnt(11)
	v_cvt_pk_bf16_f32 v4, v112, v113
	s_waitcnt vmcnt(10)
	v_cvt_pk_bf16_f32 v2, v116, v117
	v_cvt_pk_bf16_f32 v3, v118, v119
	v_cvt_pk_bf16_f32 v5, v114, v115
	s_waitcnt vmcnt(8)
	v_cvt_pk_bf16_f32 v6, v124, v125
	v_cvt_pk_bf16_f32 v7, v126, v127
	v_cvt_pk_bf16_f32 v8, v120, v121
	s_waitcnt vmcnt(4)
	v_cvt_pk_bf16_f32 v14, v140, v141
	v_cvt_pk_bf16_f32 v15, v142, v143
	v_cvt_pk_bf16_f32 v9, v122, v123
	v_cvt_pk_bf16_f32 v10, v136, v137
	v_cvt_pk_bf16_f32 v11, v138, v139
	v_cvt_pk_bf16_f32 v12, v128, v129
	v_cvt_pk_bf16_f32 v13, v130, v131
	v_cvt_pk_bf16_f32 v16, v132, v133
	v_cvt_pk_bf16_f32 v17, v134, v135
	ds_write_b128 v19, v[2:5]
	ds_write_b128 v19, v[6:9] offset:16
	ds_write_b128 v20, v[10:13] offset:18432
	ds_write_b128 v20, v[14:17] offset:18448
	v_mov_b32_e32 v14, v1
	v_mov_b32_e32 v15, v1
	v_mov_b32_e32 v2, v1
	v_mov_b32_e32 v3, v1
	v_mov_b32_e32 v4, v1
	v_mov_b32_e32 v5, v1
	v_mov_b32_e32 v6, v1
	v_mov_b32_e32 v7, v1
	v_mov_b32_e32 v8, v1
	v_mov_b32_e32 v9, v1
	v_mov_b32_e32 v10, v1
	v_mov_b32_e32 v11, v1
	v_mov_b32_e32 v12, v1
	v_mov_b32_e32 v13, v1
	v_mov_b64_e32 v[30:31], v[14:15]
	v_mov_b64_e32 v[46:47], v[14:15]
	v_mov_b64_e32 v[62:63], v[14:15]
	v_mov_b64_e32 v[78:79], v[14:15]
	v_mov_b64_e32 v[28:29], v[12:13]
	v_mov_b64_e32 v[26:27], v[10:11]
	v_mov_b64_e32 v[24:25], v[8:9]
	v_mov_b64_e32 v[22:23], v[6:7]
	v_mov_b64_e32 v[20:21], v[4:5]
	v_mov_b64_e32 v[18:19], v[2:3]
	v_mov_b64_e32 v[16:17], v[0:1]
	v_mov_b64_e32 v[44:45], v[12:13]
	v_mov_b64_e32 v[42:43], v[10:11]
	v_mov_b64_e32 v[40:41], v[8:9]
	v_mov_b64_e32 v[38:39], v[6:7]
	v_mov_b64_e32 v[36:37], v[4:5]
	v_mov_b64_e32 v[34:35], v[2:3]
	v_mov_b64_e32 v[32:33], v[0:1]
	v_mov_b64_e32 v[60:61], v[12:13]
	v_mov_b64_e32 v[58:59], v[10:11]
	v_mov_b64_e32 v[56:57], v[8:9]
	v_mov_b64_e32 v[54:55], v[6:7]
	v_mov_b64_e32 v[52:53], v[4:5]
	v_mov_b64_e32 v[50:51], v[2:3]
	v_mov_b64_e32 v[48:49], v[0:1]
	v_mov_b64_e32 v[76:77], v[12:13]
	v_mov_b64_e32 v[74:75], v[10:11]
	v_mov_b64_e32 v[72:73], v[8:9]
	v_mov_b64_e32 v[70:71], v[6:7]
	v_mov_b64_e32 v[68:69], v[4:5]
	v_mov_b64_e32 v[66:67], v[2:3]
	v_mov_b64_e32 v[64:65], v[0:1]
	s_waitcnt vmcnt(0)
	s_waitcnt lgkmcnt(0)
	s_barrier
	v_add_u32_e32 v2, s41, v186
	v_ashrrev_i32_e32 v3, 31, v2
	v_lshlrev_b64 v[2:3], 11, v[2:3]
	v_lshl_or_b32 v2, v164, 2, v2
	v_lshl_add_u64 v[4:5], s[24:25], 0, v[2:3]
	v_lshl_add_u64 v[2:3], s[26:27], 0, v[2:3]
	global_load_dwordx4 v[218:221], v[4:5], off offset:48
	global_load_dwordx4 v[222:225], v[4:5], off offset:32
	global_load_dwordx4 v[210:213], v[4:5], off offset:16
	global_load_dwordx4 v[214:217], v[4:5], off
	global_load_dwordx4 v[230:233], v[2:3], off offset:48
	global_load_dwordx4 v[238:241], v[2:3], off offset:32
	global_load_dwordx4 v[226:229], v[2:3], off offset:16
	global_load_dwordx4 v[234:237], v[2:3], off
	v_add_u32_e32 v186, 64, v186
.LBB0_947:
	s_cmpk_eq_i32 s34, 0xf000
	s_cselect_b64 s[6:7], -1, 0
	s_cmpk_lg_i32 s34, 0xf000
	s_cselect_b64 s[10:11], -1, 0
	s_cmp_gt_u32 s28, 62
	s_cbranch_scc1 .Ls2_issue_done
	s_bitcmp1_b32 s28, 0
	s_cbranch_scc1 .Ls2_issue_odd
	s_cmp_eq_u32 s28, 62
	s_cbranch_scc1 .Ls2_issue_bf16
	v_add_u32_e32 v2, s41, v186
	v_ashrrev_i32_e32 v3, 31, v2
	v_lshlrev_b64 v[2:3], 11, v[2:3]
	v_lshl_or_b32 v2, v164, 2, v2
	v_lshl_add_u64 v[4:5], s[24:25], 0, v[2:3]
	v_lshl_add_u64 v[2:3], s[26:27], 0, v[2:3]
	global_load_dwordx4 v[120:123], v[4:5], off offset:48
	global_load_dwordx4 v[124:127], v[4:5], off offset:32
	global_load_dwordx4 v[112:115], v[4:5], off offset:16
	global_load_dwordx4 v[116:119], v[4:5], off
	global_load_dwordx4 v[132:135], v[2:3], off offset:48
	global_load_dwordx4 v[140:143], v[2:3], off offset:32
	global_load_dwordx4 v[128:131], v[2:3], off offset:16
	global_load_dwordx4 v[136:139], v[2:3], off
	s_branch .Ls2_issue_done
.Ls2_issue_bf16:
	v_min_i32_e32 v0, 0x101f, v186
	v_add_u32_e32 v2, s56, v0
	v_ashrrev_i32_e32 v3, 31, v2
	v_lshlrev_b64 v[2:3], 10, v[2:3]
	v_lshl_or_b32 v2, v164, 1, v2
	v_lshl_add_u64 v[4:5], s[72:73], 0, v[2:3]
	v_lshl_add_u64 v[2:3], s[74:75], 0, v[2:3]
	global_load_dwordx4 v[112:115], v[4:5], off offset:16
	global_load_dwordx4 v[116:119], v[4:5], off
	global_load_dwordx4 v[120:123], v[2:3], off offset:16
	global_load_dwordx4 v[124:127], v[2:3], off
	s_branch .Ls2_issue_done
.Ls2_issue_odd:
	v_add_u32_e32 v2, s41, v186
	v_ashrrev_i32_e32 v3, 31, v2
	v_lshlrev_b64 v[2:3], 11, v[2:3]
	v_lshl_or_b32 v2, v164, 2, v2
	v_lshl_add_u64 v[4:5], s[24:25], 0, v[2:3]
	v_lshl_add_u64 v[2:3], s[26:27], 0, v[2:3]
	global_load_dwordx4 v[218:221], v[4:5], off offset:48
	global_load_dwordx4 v[222:225], v[4:5], off offset:32
	global_load_dwordx4 v[210:213], v[4:5], off offset:16
	global_load_dwordx4 v[214:217], v[4:5], off
	global_load_dwordx4 v[230:233], v[2:3], off offset:48
	global_load_dwordx4 v[238:241], v[2:3], off offset:32
	global_load_dwordx4 v[226:229], v[2:3], off offset:16
	global_load_dwordx4 v[234:237], v[2:3], off
.Ls2_issue_done:
.LBB0_952:
	s_and_b32 s12, s28, 3
	s_cmp_lg_u32 s12, s30
	s_cbranch_scc1 .LBB0_956
	s_bitcmp1_b32 s28, 0
	s_cselect_b32 s12, 0x9800, 0
	s_add_i32 s12, s12, 0
	s_mul_i32 s13, s40, 0x2400
	s_add_i32 s13, s12, s13
	v_add3_u32 v0, s13, v184, v166
	ds_read_b128 v[2:5], v0 offset:4608
	ds_read_b128 v[6:9], v0
	ds_read_b128 v[10:13], v0 offset:32
	s_xor_b32 s37, s84, 0x80000000
	s_waitcnt lgkmcnt(2)
	v_mfma_f32_32x32x16_bf16 v[80:95], v[2:5], v[156:159], 0
	ds_read_b128 v[2:5], v0 offset:4640
	s_xor_b32 s36, s57, 0x80000000
	s_waitcnt lgkmcnt(2)
	v_mfma_f32_32x32x16_bf16 v[96:111], v[6:9], v[156:159], 0
	s_waitcnt lgkmcnt(1)
	v_mfma_f32_32x32x16_bf16 v[96:111], v[10:13], v[152:155], v[96:111]
	s_waitcnt lgkmcnt(0)
	v_mfma_f32_32x32x16_bf16 v[80:95], v[2:5], v[152:155], v[80:95]
	ds_read_b128 v[2:5], v0 offset:64
	ds_read_b128 v[6:9], v0 offset:4672
	s_waitcnt lgkmcnt(1)
	v_mfma_f32_32x32x16_bf16 v[96:111], v[2:5], v[148:151], v[96:111]
	s_waitcnt lgkmcnt(0)
	v_mfma_f32_32x32x16_bf16 v[80:95], v[6:9], v[148:151], v[80:95]
	ds_read_b128 v[2:5], v0 offset:96
	ds_read_b128 v[6:9], v0 offset:4704
	s_waitcnt lgkmcnt(1)
	v_mfma_f32_32x32x16_bf16 v[96:111], v[2:5], v[144:147], v[96:111]
	s_waitcnt lgkmcnt(0)
; __device__ __forceinline__ float fexp2(float x) { return __builtin_amdgcn_exp2f(x); }
; template <int NEB>
; __device__ __forceinline__ void softmax_tile(f32x16& X0, f32x16& X1, float& m, float& l, f32x16 (&OT)[NEB]) {
;     float mx = X0[0];
; #pragma unroll
;     for (int r = 1; r < 16; ++r) mx = fmaxf(mx, X0[r]);
; #pragma unroll
;     for (int r = 0; r < 16; ++r) mx = fmaxf(mx, X1[r]);
;     mx = fmaxf(mx, __shfl_xor(mx, 32));
;     if (__any(mx > m + 8.f)) {
;         const float mn = fmaxf(m, mx), alpha = fexp2(m - mn); m = mn; l *= alpha;
; #pragma unroll
;         for (int e = 0; e < NEB; ++e) OT[e] = OT[e] * alpha;
;     }
	v_mfma_f32_32x32x16_bf16 v[80:95], v[6:9], v[144:147], v[80:95]
	v_add_u32_e32 v9, s34, v185
	v_add_u32_e32 v2, 0xfff, v9
	v_cvt_f32_i32_e32 v2, v2
	v_add_u32_e32 v0, 0x1000, v9
	v_cvt_f32_i32_e32 v0, v0
	v_add_u32_e32 v4, 0xff8, v9
	s_nop 3
	v_fma_f32 v7, -v181, |v2|, v97
	v_add_u32_e32 v2, 0xffe, v9
	v_cvt_f32_i32_e32 v2, v2
	v_fma_f32 v6, -v181, |v0|, v96
	v_add_u32_e32 v96, 0xfef, v9
	v_cvt_f32_i32_e32 v96, v96
	v_fma_f32 v8, -v181, |v2|, v98
	v_add_u32_e32 v2, 0xffd, v9
	v_cvt_f32_i32_e32 v2, v2
	v_cvt_f32_i32_e32 v4, v4
	v_add_u32_e32 v15, 0xff5, v9
	v_cvt_f32_i32_e32 v15, v15
	v_fma_f32 v10, -v181, |v2|, v99
	v_fma_f32 v99, -v181, |v96|, v105
	v_add_u32_e32 v96, 0xfee, v9
	v_fma_f32 v11, -v181, |v4|, v100
	v_add_u32_e32 v4, 0xff7, v9
	v_cvt_f32_i32_e32 v96, v96
	v_add_u32_e32 v100, 0xfe8, v9
	v_cvt_f32_i32_e32 v4, v4
	v_cvt_f32_i32_e32 v100, v100
	v_fma_f32 v98, -v181, |v15|, v103
	v_add_u32_e32 v15, 0xff0, v9
	v_add_f32_e32 v0, 0xc2000000, v0
	v_cvt_f32_i32_e32 v15, v15
	v_fma_f32 v97, -v181, |v96|, v106
	v_add_u32_e32 v96, 0xfed, v9
	v_pk_add_f32 v[2:3], v[0:1], s[38:39] op_sel_hi:[0,1]
	v_fma_f32 v12, -v181, |v4|, v101
	v_cvt_f32_i32_e32 v96, v96
	v_fma_f32 v101, -v181, |v100|, v108
	v_add_u32_e32 v100, 0xfe7, v9
	v_pk_add_f32 v[4:5], v[0:1], s[46:47] op_sel_hi:[0,1]
	v_cvt_f32_i32_e32 v100, v100
	v_and_b32_e32 v3, 0x7fffffff, v3
	v_and_b32_e32 v2, 0x7fffffff, v2
	v_pk_add_f32 v[188:189], v[0:1], s[48:49] op_sel_hi:[0,1]
	v_and_b32_e32 v5, 0x7fffffff, v5
	v_and_b32_e32 v4, 0x7fffffff, v4
	v_pk_fma_f32 v[192:193], s[36:37], v[2:3], v[82:83]
	s_xor_b32 s37, s86, 0x80000000
	s_xor_b32 s36, s85, 0x80000000
	v_add_u32_e32 v14, 0xff6, v9
	v_fma_f32 v15, -v181, |v15|, v104
	v_pk_add_f32 v[104:105], v[0:1], s[50:51] op_sel_hi:[0,1]
	v_and_b32_e32 v189, 0x7fffffff, v189
	v_and_b32_e32 v188, 0x7fffffff, v188
	v_pk_fma_f32 v[4:5], s[36:37], v[4:5], v[84:85]
	s_xor_b32 s37, s91, 0x80000000
	s_xor_b32 s36, s87, 0x80000000
	v_cvt_f32_i32_e32 v14, v14
	v_fma_f32 v96, -v181, |v96|, v107
	v_pk_add_f32 v[106:107], v[0:1], s[78:79] op_sel_hi:[0,1]
	v_and_b32_e32 v105, 0x7fffffff, v105
	v_and_b32_e32 v104, 0x7fffffff, v104
	v_pk_fma_f32 v[82:83], s[36:37], v[188:189], v[86:87]
	s_xor_b32 s37, s93, 0x80000000
	s_xor_b32 s36, s92, 0x80000000
	v_add_f32_e32 v13, -1.0, v0
	v_fma_f32 v100, -v181, |v100|, v109
	v_pk_add_f32 v[108:109], v[0:1], s[80:81] op_sel_hi:[0,1]
	v_and_b32_e32 v107, 0x7fffffff, v107
	v_and_b32_e32 v106, 0x7fffffff, v106
	v_pk_fma_f32 v[84:85], s[36:37], v[104:105], v[88:89]
	s_xor_b32 s37, s95, 0x80000000
	s_xor_b32 s36, s94, 0x80000000
	v_and_b32_e32 v109, 0x7fffffff, v109
	v_and_b32_e32 v108, 0x7fffffff, v108
	v_and_b32_e32 v190, 0x7fffffff, v0
	v_and_b32_e32 v191, 0x7fffffff, v13
	v_pk_fma_f32 v[2:3], s[36:37], v[106:107], v[90:91]
	s_xor_b32 s37, s97, 0x80000000
	s_xor_b32 s36, s96, 0x80000000
	v_pk_fma_f32 v[86:87], s[36:37], v[108:109], v[92:93]
	v_pk_fma_f32 v[92:93], s[8:9], v[190:191], v[80:81] neg_lo:[1,0,0] neg_hi:[1,0,0]
	v_cndmask_b32_e64 v81, v82, v174, s[6:7]
	v_cndmask_b32_e64 v82, v5, v174, s[6:7]
	v_max_f32_e32 v5, v6, v7
	v_fma_f32 v14, -v181, |v14|, v102
	v_add_u32_e32 v102, 0xfe6, v9
	v_add_u32_e32 v9, 0xfe5, v9
	v_max3_f32 v5, v5, v8, v10
	v_cvt_f32_i32_e32 v102, v102
	v_cvt_f32_i32_e32 v9, v9
	v_max3_f32 v5, v5, v11, v12
	v_max3_f32 v5, v5, v14, v98
	v_max3_f32 v5, v5, v15, v99
	v_max3_f32 v5, v5, v97, v96
	v_fma_f32 v102, -v181, |v102|, v110
	v_fma_f32 v103, -v181, |v9|, v111
	v_max3_f32 v5, v5, v101, v100
	v_pk_add_f32 v[110:111], v[0:1], s[82:83] op_sel_hi:[0,1]
	v_cndmask_b32_e64 v13, v4, v174, s[6:7]
	v_cndmask_b32_e64 v0, v92, v174, s[6:7]
	v_cndmask_b32_e64 v4, v93, v174, s[6:7]
	v_max3_f32 v5, v5, v102, v103
	v_cndmask_b32_e64 v80, v83, v174, s[6:7]
	v_cndmask_b32_e64 v9, v192, v174, s[6:7]
	v_cndmask_b32_e64 v83, v193, v174, s[6:7]
	v_max3_f32 v5, v5, v0, v4
	v_and_b32_e32 v111, 0x7fffffff, v111
	v_and_b32_e32 v110, 0x7fffffff, v110
	s_xor_b32 s37, s15, 0x80000000
	s_xor_b32 s36, s14, 0x80000000
	v_max3_f32 v5, v5, v9, v83
	v_pk_fma_f32 v[88:89], s[36:37], v[110:111], v[94:95]
	v_max3_f32 v5, v5, v13, v82
	v_cndmask_b32_e64 v91, v88, v174, s[6:7]
	v_cndmask_b32_e64 v90, v89, v174, s[6:7]
	v_cndmask_b32_e64 v89, v86, v174, s[6:7]
	v_cndmask_b32_e64 v88, v87, v174, s[6:7]
	v_cndmask_b32_e64 v87, v2, v174, s[6:7]
	v_cndmask_b32_e64 v86, v3, v174, s[6:7]
	v_cndmask_b32_e64 v3, v84, v174, s[6:7]
	v_cndmask_b32_e64 v2, v85, v174, s[6:7]
	v_max3_f32 v5, v5, v81, v80
	v_max3_f32 v5, v5, v3, v2
	v_max3_f32 v5, v5, v87, v86
	v_max3_f32 v5, v5, v89, v88
	v_max3_f32 v5, v5, v91, v90
	ds_bpermute_b32 v84, v171, v5
	s_waitcnt lgkmcnt(0)
	v_max_f32_e32 v84, v84, v84
	v_max_f32_e32 v5, v5, v84
	v_add_f32_e32 v84, 0x41000000, v168
	v_cmp_gt_f32_e32 vcc, v5, v84
	s_cbranch_vccz .LBB0_955
	v_max_f32_e32 v5, v5, v5
	v_max_f32_e32 v84, v168, v168
	v_max_f32_e32 v5, v84, v5
	v_sub_f32_e32 v84, v168, v5
	v_exp_f32_e32 v84, v84
	v_mov_b32_e32 v168, v5
	v_mul_f32_e32 v187, v187, v84
	v_pk_mul_f32 v[78:79], v[78:79], v[84:85] op_sel_hi:[1,0]
	v_pk_mul_f32 v[76:77], v[76:77], v[84:85] op_sel_hi:[1,0]
	v_pk_mul_f32 v[74:75], v[74:75], v[84:85] op_sel_hi:[1,0]
	v_pk_mul_f32 v[72:73], v[72:73], v[84:85] op_sel_hi:[1,0]
	v_pk_mul_f32 v[70:71], v[70:71], v[84:85] op_sel_hi:[1,0]
	v_pk_mul_f32 v[68:69], v[68:69], v[84:85] op_sel_hi:[1,0]
	v_pk_mul_f32 v[66:67], v[66:67], v[84:85] op_sel_hi:[1,0]
	v_pk_mul_f32 v[64:65], v[64:65], v[84:85] op_sel_hi:[1,0]
	v_pk_mul_f32 v[62:63], v[62:63], v[84:85] op_sel_hi:[1,0]
	v_pk_mul_f32 v[60:61], v[60:61], v[84:85] op_sel_hi:[1,0]
	v_pk_mul_f32 v[58:59], v[58:59], v[84:85] op_sel_hi:[1,0]
	v_pk_mul_f32 v[56:57], v[56:57], v[84:85] op_sel_hi:[1,0]
	v_pk_mul_f32 v[54:55], v[54:55], v[84:85] op_sel_hi:[1,0]
	v_pk_mul_f32 v[52:53], v[52:53], v[84:85] op_sel_hi:[1,0]
	v_pk_mul_f32 v[50:51], v[50:51], v[84:85] op_sel_hi:[1,0]
	v_pk_mul_f32 v[48:49], v[48:49], v[84:85] op_sel_hi:[1,0]
	v_pk_mul_f32 v[46:47], v[46:47], v[84:85] op_sel_hi:[1,0]
	v_pk_mul_f32 v[44:45], v[44:45], v[84:85] op_sel_hi:[1,0]
	v_pk_mul_f32 v[42:43], v[42:43], v[84:85] op_sel_hi:[1,0]
	v_pk_mul_f32 v[40:41], v[40:41], v[84:85] op_sel_hi:[1,0]
	v_pk_mul_f32 v[38:39], v[38:39], v[84:85] op_sel_hi:[1,0]
	v_pk_mul_f32 v[36:37], v[36:37], v[84:85] op_sel_hi:[1,0]
	v_pk_mul_f32 v[34:35], v[34:35], v[84:85] op_sel_hi:[1,0]
	v_pk_mul_f32 v[32:33], v[32:33], v[84:85] op_sel_hi:[1,0]
	v_pk_mul_f32 v[30:31], v[30:31], v[84:85] op_sel_hi:[1,0]
	v_pk_mul_f32 v[28:29], v[28:29], v[84:85] op_sel_hi:[1,0]
	v_pk_mul_f32 v[26:27], v[26:27], v[84:85] op_sel_hi:[1,0]
	v_pk_mul_f32 v[24:25], v[24:25], v[84:85] op_sel_hi:[1,0]
	v_pk_mul_f32 v[22:23], v[22:23], v[84:85] op_sel_hi:[1,0]
	v_pk_mul_f32 v[20:21], v[20:21], v[84:85] op_sel_hi:[1,0]
	v_pk_mul_f32 v[18:19], v[18:19], v[84:85] op_sel_hi:[1,0]
	v_pk_mul_f32 v[16:17], v[16:17], v[84:85] op_sel_hi:[1,0]

.LBB0_956:
	s_andn2_b64 vcc, exec, s[10:11]
	s_add_i32 s6, s28, 1
	s_cbranch_vccnz .LBB0_960
	s_bitcmp1_b32 s28, 0
	s_cbranch_scc1 .Ls2_write_odd
	s_cmp_eq_u32 s28, 62
	s_cbranch_scc1 .Ls2_w_e4
	s_waitcnt vmcnt(8)
	s_branch .Ls2_w_e
.Ls2_w_e4:
	s_waitcnt vmcnt(4)
.Ls2_w_e:
	v_cvt_pk_bf16_f32 v2, v214, v215
	v_cvt_pk_bf16_f32 v3, v216, v217
	v_cvt_pk_bf16_f32 v4, v210, v211
	v_cvt_pk_bf16_f32 v5, v212, v213
	v_cvt_pk_bf16_f32 v6, v222, v223
	v_cvt_pk_bf16_f32 v7, v224, v225
	v_cvt_pk_bf16_f32 v8, v218, v219
	v_cvt_pk_bf16_f32 v9, v220, v221
	v_cvt_pk_bf16_f32 v10, v234, v235
	v_cvt_pk_bf16_f32 v11, v236, v237
	v_cvt_pk_bf16_f32 v12, v226, v227
	v_cvt_pk_bf16_f32 v13, v228, v229
	v_cvt_pk_bf16_f32 v80, v238, v239
	v_cvt_pk_bf16_f32 v81, v240, v241
	v_cvt_pk_bf16_f32 v82, v230, v231
	v_cvt_pk_bf16_f32 v83, v232, v233
	s_branch .LBB0_959
.Ls2_write_odd:
	s_cmp_eq_u32 s28, 63
	s_cbranch_scc1 .Ls2_w_o_bf16
	s_waitcnt vmcnt(8)
	v_cvt_pk_bf16_f32 v2, v116, v117
	v_cvt_pk_bf16_f32 v3, v118, v119
	v_cvt_pk_bf16_f32 v4, v112, v113
	v_cvt_pk_bf16_f32 v5, v114, v115
	v_cvt_pk_bf16_f32 v6, v124, v125
	v_cvt_pk_bf16_f32 v7, v126, v127
	v_cvt_pk_bf16_f32 v8, v120, v121
	v_cvt_pk_bf16_f32 v9, v122, v123
	v_cvt_pk_bf16_f32 v10, v136, v137
	v_cvt_pk_bf16_f32 v11, v138, v139
	v_cvt_pk_bf16_f32 v12, v128, v129
	v_cvt_pk_bf16_f32 v13, v130, v131
	v_cvt_pk_bf16_f32 v80, v140, v141
	v_cvt_pk_bf16_f32 v81, v142, v143
	v_cvt_pk_bf16_f32 v82, v132, v133
	v_cvt_pk_bf16_f32 v83, v134, v135
	s_branch .LBB0_959
.Ls2_w_o_bf16:
	s_waitcnt vmcnt(0)
	v_mov_b64_e32 v[80:81], v[120:121]
	v_mov_b64_e32 v[10:11], v[124:125]
	v_mov_b64_e32 v[6:7], v[112:113]
	v_mov_b64_e32 v[2:3], v[116:117]
	v_mov_b64_e32 v[82:83], v[122:123]
	v_mov_b64_e32 v[12:13], v[126:127]
	v_mov_b64_e32 v[8:9], v[114:115]
	v_mov_b64_e32 v[4:5], v[118:119]

; __global__ void __launch_bounds__(512, 2) mega(Params p) {
;     ...
; #pragma unroll
;     for (int i = 0; i < 34; ++i) { __builtin_assume(!__builtin_amdgcn_is_shared((const void*)p.in[i])); __builtin_assume(!__builtin_amdgcn_is_private((const void*)p.in[i])); }
;     __builtin_assume(!__builtin_amdgcn_is_shared((const void*)p.out)); __builtin_assume(!__builtin_amdgcn_is_private((const void*)p.out));
;     __builtin_assume(!__builtin_amdgcn_is_shared((const void*)p.ws)); __builtin_assume(!__builtin_amdgcn_is_private((const void*)p.ws));
;     ...
;     extern __shared__ __attribute__((aligned(16))) unsigned char lds_raw[];
	.amdhsa_kernel _Z4mega6Params
		.amdhsa_group_segment_fixed_size 0
		.amdhsa_private_segment_fixed_size 0
		.amdhsa_kernarg_size 552
		.amdhsa_user_sgpr_count 2
		.amdhsa_user_sgpr_dispatch_ptr 0
		.amdhsa_user_sgpr_queue_ptr 0
		.amdhsa_user_sgpr_kernarg_segment_ptr 1
		.amdhsa_user_sgpr_dispatch_id 0
		.amdhsa_user_sgpr_kernarg_preload_length 0
		.amdhsa_user_sgpr_kernarg_preload_offset 0
		.amdhsa_user_sgpr_private_segment_size 0
		.amdhsa_uses_dynamic_stack 0
		.amdhsa_enable_private_segment 0
		.amdhsa_system_sgpr_workgroup_id_x 1
		.amdhsa_system_sgpr_workgroup_id_y 0
		.amdhsa_system_sgpr_workgroup_id_z 0
		.amdhsa_system_sgpr_workgroup_info 0
		.amdhsa_system_vgpr_workitem_id 2
		.amdhsa_next_free_vgpr 253
		.amdhsa_next_free_sgpr 100
		.amdhsa_accum_offset 256
		.amdhsa_reserve_vcc 1
		.amdhsa_float_round_mode_32 0
		.amdhsa_float_round_mode_16_64 0
		.amdhsa_float_denorm_mode_32 3
		.amdhsa_float_denorm_mode_16_64 3
		.amdhsa_dx10_clamp 1
		.amdhsa_ieee_mode 1
		.amdhsa_fp16_overflow 0
		.amdhsa_tg_split 0
		.amdhsa_exception_fp_ieee_invalid_op 0
		.amdhsa_exception_fp_denorm_src 0
		.amdhsa_exception_fp_ieee_div_zero 0
		.amdhsa_exception_fp_ieee_overflow 0
		.amdhsa_exception_fp_ieee_underflow 0
		.amdhsa_exception_fp_ieee_inexact 0
		.amdhsa_exception_int_div_zero 0
	.end_amdhsa_kernel

; __global__ void __launch_bounds__(512, 2) mega(Params p) {
;     ...
; #pragma unroll
;     for (int i = 0; i < 34; ++i) { __builtin_assume(!__builtin_amdgcn_is_shared((const void*)p.in[i])); __builtin_assume(!__builtin_amdgcn_is_private((const void*)p.in[i])); }
;     __builtin_assume(!__builtin_amdgcn_is_shared((const void*)p.out)); __builtin_assume(!__builtin_amdgcn_is_private((const void*)p.out));
;     __builtin_assume(!__builtin_amdgcn_is_shared((const void*)p.ws)); __builtin_assume(!__builtin_amdgcn_is_private((const void*)p.ws));
;     ...
;     extern __shared__ __attribute__((aligned(16))) unsigned char lds_raw[];
amdhsa.kernels:
  - .agpr_count:     0
    .args:
      - .offset:         0
        .size:           296
        .value_kind:     by_value
      - .offset:         296
        .size:           4
        .value_kind:     hidden_block_count_x
      - .offset:         300
        .size:           4
        .value_kind:     hidden_block_count_y
      - .offset:         304
        .size:           4
        .value_kind:     hidden_block_count_z
      - .offset:         308
        .size:           2
        .value_kind:     hidden_group_size_x
      - .offset:         310
        .size:           2
        .value_kind:     hidden_group_size_y
      - .offset:         312
        .size:           2
        .value_kind:     hidden_group_size_z
      - .offset:         314
        .size:           2
        .value_kind:     hidden_remainder_x
      - .offset:         316
        .size:           2
        .value_kind:     hidden_remainder_y
      - .offset:         318
        .size:           2
        .value_kind:     hidden_remainder_z
      - .offset:         336
        .size:           8
        .value_kind:     hidden_global_offset_x
      - .offset:         344
        .size:           8
        .value_kind:     hidden_global_offset_y
      - .offset:         352
        .size:           8
        .value_kind:     hidden_global_offset_z
      - .offset:         360
        .size:           2
        .value_kind:     hidden_grid_dims
      - .offset:         384
        .size:           8
        .value_kind:     hidden_multigrid_sync_arg
      - .offset:         416
        .size:           4
        .value_kind:     hidden_dynamic_lds_size
    .group_segment_fixed_size: 0
    .kernarg_segment_align: 8
    .kernarg_segment_size: 552
    .language:       OpenCL C
    .language_version:
      - 2
      - 0
    .max_flat_workgroup_size: 512
    .name:           _Z4mega6Params
    .private_segment_fixed_size: 0
    .sgpr_count:     106
    .sgpr_spill_count: 24
    .symbol:         _Z4mega6Params.kd
    .uniform_work_group_size: 1
    .uses_dynamic_stack: false
    .vgpr_count:     253
    .vgpr_spill_count: 0
    .wavefront_size: 64
